# DA main loop role stagger: waves 4-7 defer PV by one step, second barrier per step
# speedup vs baseline: 1.0037x; 1.0037x over previous
.LBB0_296:
	v_readlane_b32 s99, v239, 60
	s_nop 3
	s_cmp_lt_u32 s99, 4
	s_cbranch_scc0 .Lds_B296
.Lds_A296:
	s_bitcmp1_b32 s0, 0
	s_cselect_b32 s50, 0x8800, 0
	v_add3_u32 v0, s50, v170, v171
	s_waitcnt vmcnt(3)
	ds_write_b128 v0, v[128:131]
	s_waitcnt vmcnt(2)
	ds_write_b128 v0, v[136:139] offset:8192
	v_add_u32_e32 v0, s50, v147
	v_add3_u32 v0, v0, v144, v172
	v_add_u32_e32 v2, 0x4000, v0
	s_waitcnt vmcnt(1)
	ds_write2_b64 v2, v[132:133], v[134:135] offset1:2
	v_add_co_u32_e32 v2, vcc, s47, v162
	v_add_u32_e32 v0, 0x6000, v0
	s_nop 0
	v_addc_co_u32_e32 v3, vcc, -1, v163, vcc
	s_waitcnt vmcnt(0)
	ds_write2_b64 v0, v[140:141], v[142:143] offset0:128 offset1:130
	s_waitcnt lgkmcnt(0)
	s_barrier
	global_load_dwordx4 v[128:131], v[2:3], off
	global_load_dwordx4 v[136:139], v[162:163], off
	v_lshl_add_u64 v[2:3], v[164:165], 0, s[8:9]
	v_add_co_u32_e32 v4, vcc, s38, v2
	s_nop 0
	s_nop 0
	v_addc_co_u32_e32 v5, vcc, 0, v3, vcc
	global_load_dwordx4 v[132:135], v[2:3], off offset:128
	global_load_dwordx4 v[140:143], v[4:5], off offset:128
	v_add_u32_e32 v0, s50, v173
	v_add_u32_e32 v6, v0, v174
	v_add_u32_e32 v14, v0, v175
	ds_read_b128 v[2:5], v6
	ds_read_b128 v[6:9], v6 offset:8192
	ds_read_b128 v[10:13], v14
	ds_read_b128 v[186:189], v14 offset:8192
	v_add_u32_e32 v14, v0, v176
	v_add_u32_e32 v0, v0, v177
	ds_read_b128 v[190:193], v14
	ds_read_b128 v[194:197], v14 offset:8192
	ds_read_b128 v[198:201], v0
	ds_read_b128 v[202:205], v0 offset:8192
	s_waitcnt lgkmcnt(7)
	v_mfma_f32_32x32x16_bf16 v[96:111], v[2:5], v[124:127], 0
	s_waitcnt lgkmcnt(6)
	v_mfma_f32_32x32x16_bf16 v[80:95], v[6:9], v[124:127], 0
	s_waitcnt lgkmcnt(5)
	v_mfma_f32_32x32x16_bf16 v[96:111], v[10:13], v[120:123], v[96:111]
	s_waitcnt lgkmcnt(4)
	v_mfma_f32_32x32x16_bf16 v[80:95], v[186:189], v[120:123], v[80:95]
	s_waitcnt lgkmcnt(3)
	v_mfma_f32_32x32x16_bf16 v[96:111], v[190:193], v[116:119], v[96:111]
	s_waitcnt lgkmcnt(2)
	v_mfma_f32_32x32x16_bf16 v[80:95], v[194:197], v[116:119], v[80:95]
	s_waitcnt lgkmcnt(1)
	v_mfma_f32_32x32x16_bf16 v[96:111], v[198:201], v[112:115], v[96:111]
	s_waitcnt lgkmcnt(0)
	v_mfma_f32_32x32x16_bf16 v[80:95], v[202:205], v[112:115], v[80:95]
	s_nop 9
	v_max_f32_e32 v0, v97, v97
	v_max_f32_e32 v2, v96, v96
	v_max_f32_e32 v0, v2, v0
	v_max3_f32 v0, v0, v98, v99
	v_max3_f32 v0, v0, v100, v101
	v_max3_f32 v0, v0, v102, v103
	v_max3_f32 v0, v0, v104, v105
	v_max3_f32 v0, v0, v106, v107
	v_max3_f32 v0, v0, v108, v109
	v_max3_f32 v0, v0, v110, v111
	v_max3_f32 v0, v0, v80, v81
	v_max3_f32 v0, v0, v82, v83
	v_max3_f32 v0, v0, v84, v85
	v_max3_f32 v0, v0, v86, v87
	v_max3_f32 v0, v0, v88, v89
	v_max3_f32 v0, v0, v90, v91
	v_max3_f32 v0, v0, v92, v93
	v_max3_f32 v0, v0, v94, v95
	v_mov_b32_e32 v2, v0
	s_nop 1
	v_permlane32_swap_b32_e32 v0, v2
	v_max_f32_e32 v2, v2, v2
	v_max_f32_e32 v0, v0, v0
	v_max_f32_e32 v0, v0, v2
	v_add_f32_e32 v2, 0x40b00000, v155
	v_cmp_gt_f32_e32 vcc, v0, v2
	s_cbranch_vccz .Lds_A295
	s_nop 0
	v_cndmask_b32_e32 v2, v155, v0, vcc
	v_sub_f32_e32 v0, v155, v2
	v_mul_f32_e32 v0, 0x3fb8aa3b, v0
	v_exp_f32_e32 v0, v0
	v_mov_b32_e32 v155, v2
	v_pk_mul_f32 v[78:79], v[78:79], v[0:1] op_sel_hi:[1,0]
	v_pk_mul_f32 v[76:77], v[76:77], v[0:1] op_sel_hi:[1,0]
	v_pk_mul_f32 v[74:75], v[74:75], v[0:1] op_sel_hi:[1,0]
	v_pk_mul_f32 v[72:73], v[72:73], v[0:1] op_sel_hi:[1,0]
	v_pk_mul_f32 v[70:71], v[70:71], v[0:1] op_sel_hi:[1,0]
	v_pk_mul_f32 v[68:69], v[68:69], v[0:1] op_sel_hi:[1,0]
	v_pk_mul_f32 v[66:67], v[66:67], v[0:1] op_sel_hi:[1,0]
	v_pk_mul_f32 v[64:65], v[64:65], v[0:1] op_sel_hi:[1,0]
	v_pk_mul_f32 v[62:63], v[62:63], v[0:1] op_sel_hi:[1,0]
	v_pk_mul_f32 v[60:61], v[60:61], v[0:1] op_sel_hi:[1,0]
	v_pk_mul_f32 v[58:59], v[58:59], v[0:1] op_sel_hi:[1,0]
	v_pk_mul_f32 v[56:57], v[56:57], v[0:1] op_sel_hi:[1,0]
	v_pk_mul_f32 v[54:55], v[54:55], v[0:1] op_sel_hi:[1,0]
	v_pk_mul_f32 v[52:53], v[52:53], v[0:1] op_sel_hi:[1,0]
	v_pk_mul_f32 v[50:51], v[50:51], v[0:1] op_sel_hi:[1,0]
	v_pk_mul_f32 v[48:49], v[48:49], v[0:1] op_sel_hi:[1,0]
	v_pk_mul_f32 v[46:47], v[46:47], v[0:1] op_sel_hi:[1,0]
	v_pk_mul_f32 v[44:45], v[44:45], v[0:1] op_sel_hi:[1,0]
	v_pk_mul_f32 v[42:43], v[42:43], v[0:1] op_sel_hi:[1,0]
	v_pk_mul_f32 v[40:41], v[40:41], v[0:1] op_sel_hi:[1,0]
	v_pk_mul_f32 v[38:39], v[38:39], v[0:1] op_sel_hi:[1,0]
	v_pk_mul_f32 v[36:37], v[36:37], v[0:1] op_sel_hi:[1,0]
	v_pk_mul_f32 v[34:35], v[34:35], v[0:1] op_sel_hi:[1,0]
	v_pk_mul_f32 v[32:33], v[32:33], v[0:1] op_sel_hi:[1,0]
	v_pk_mul_f32 v[30:31], v[30:31], v[0:1] op_sel_hi:[1,0]
	v_pk_mul_f32 v[28:29], v[28:29], v[0:1] op_sel_hi:[1,0]
	v_pk_mul_f32 v[26:27], v[26:27], v[0:1] op_sel_hi:[1,0]
	v_pk_mul_f32 v[24:25], v[24:25], v[0:1] op_sel_hi:[1,0]
	v_pk_mul_f32 v[22:23], v[22:23], v[0:1] op_sel_hi:[1,0]
	v_pk_mul_f32 v[20:21], v[20:21], v[0:1] op_sel_hi:[1,0]
	v_pk_mul_f32 v[18:19], v[18:19], v[0:1] op_sel_hi:[1,0]
	v_pk_mul_f32 v[16:17], v[16:17], v[0:1] op_sel_hi:[1,0]
	v_mul_f32_e32 v160, v160, v0
	s_branch .Lds_A295
.Lds_A295:
	v_mul_f32_e32 v161, 0xbfb8aa3b, v155
	v_fmamk_f32 v0, v96, 0x3fb8aa3b, v161
	v_exp_f32_e32 v0, v0
	v_fmamk_f32 v2, v97, 0x3fb8aa3b, v161
	v_exp_f32_e32 v2, v2
	v_fmamk_f32 v3, v98, 0x3fb8aa3b, v161
	v_exp_f32_e32 v3, v3
	v_fmamk_f32 v4, v99, 0x3fb8aa3b, v161
	v_exp_f32_e32 v4, v4
	v_fmamk_f32 v6, v100, 0x3fb8aa3b, v161
	v_add_f32_e32 v5, 0, v0
	v_exp_f32_e32 v6, v6
	v_fmamk_f32 v7, v101, 0x3fb8aa3b, v161
	v_add_f32_e32 v5, v2, v5
	v_exp_f32_e32 v7, v7
	v_fmamk_f32 v8, v102, 0x3fb8aa3b, v161
	v_add_f32_e32 v5, v3, v5
	v_exp_f32_e32 v8, v8
	v_fmamk_f32 v9, v103, 0x3fb8aa3b, v161
	v_add_f32_e32 v5, v4, v5
	v_exp_f32_e32 v9, v9
	v_fmamk_f32 v10, v104, 0x3fb8aa3b, v161
	v_add_f32_e32 v5, v6, v5
	v_exp_f32_e32 v10, v10
	v_fmamk_f32 v11, v105, 0x3fb8aa3b, v161
	v_add_f32_e32 v5, v7, v5
	v_exp_f32_e32 v11, v11
	v_fmamk_f32 v12, v106, 0x3fb8aa3b, v161
	v_add_f32_e32 v5, v8, v5
	v_exp_f32_e32 v12, v12
	v_fmamk_f32 v13, v107, 0x3fb8aa3b, v161
	v_add_f32_e32 v5, v9, v5
	v_exp_f32_e32 v13, v13
	v_fmamk_f32 v14, v108, 0x3fb8aa3b, v161
	v_add_f32_e32 v5, v10, v5
	v_exp_f32_e32 v14, v14
	v_fmamk_f32 v15, v109, 0x3fb8aa3b, v161
	v_add_f32_e32 v5, v11, v5
	v_exp_f32_e32 v15, v15
	v_fmamk_f32 v96, v110, 0x3fb8aa3b, v161
	v_add_f32_e32 v5, v12, v5
	v_exp_f32_e32 v96, v96
	v_fmamk_f32 v97, v111, 0x3fb8aa3b, v161
	v_add_f32_e32 v5, v13, v5
	v_exp_f32_e32 v97, v97
	v_add_f32_e32 v5, v14, v5
	v_add_f32_e32 v5, v15, v5
	v_add_f32_e32 v5, v96, v5
	v_add_f32_e32 v98, v97, v5
	v_fmamk_f32 v5, v80, 0x3fb8aa3b, v161
	v_exp_f32_e32 v99, v5
	v_fmamk_f32 v5, v81, 0x3fb8aa3b, v161
	v_exp_f32_e32 v100, v5
	v_fmamk_f32 v5, v82, 0x3fb8aa3b, v161
	v_exp_f32_e32 v101, v5
	v_fmamk_f32 v5, v83, 0x3fb8aa3b, v161
	v_exp_f32_e32 v102, v5
	v_fmamk_f32 v5, v84, 0x3fb8aa3b, v161
	v_exp_f32_e32 v84, v5
	v_fmamk_f32 v5, v85, 0x3fb8aa3b, v161
	v_cvt_pk_bf16_f32 v2, v0, v2
	v_add_f32_e32 v0, v99, v98
	v_exp_f32_e32 v85, v5
	v_fmamk_f32 v5, v86, 0x3fb8aa3b, v161
	v_add_f32_e32 v0, v100, v0
	v_exp_f32_e32 v86, v5
	v_fmamk_f32 v5, v87, 0x3fb8aa3b, v161
	v_add_f32_e32 v0, v101, v0
	v_exp_f32_e32 v87, v5
	v_fmamk_f32 v5, v88, 0x3fb8aa3b, v161
	v_add_f32_e32 v0, v102, v0
	v_exp_f32_e32 v88, v5
	v_fmamk_f32 v5, v89, 0x3fb8aa3b, v161
	v_add_f32_e32 v0, v84, v0
	v_exp_f32_e32 v89, v5
	v_fmamk_f32 v5, v90, 0x3fb8aa3b, v161
	v_add_f32_e32 v0, v85, v0
	v_exp_f32_e32 v90, v5
	v_fmamk_f32 v5, v91, 0x3fb8aa3b, v161
	v_add_f32_e32 v0, v86, v0
	v_exp_f32_e32 v91, v5
	v_fmamk_f32 v5, v92, 0x3fb8aa3b, v161
	v_add_f32_e32 v0, v87, v0
	v_exp_f32_e32 v92, v5
	v_fmamk_f32 v5, v93, 0x3fb8aa3b, v161
	v_add_f32_e32 v0, v88, v0
	v_exp_f32_e32 v93, v5
	v_fmamk_f32 v5, v94, 0x3fb8aa3b, v161
	v_add_f32_e32 v0, v89, v0
	v_exp_f32_e32 v94, v5
	v_fmamk_f32 v5, v95, 0x3fb8aa3b, v161
	v_add_f32_e32 v0, v90, v0
	v_exp_f32_e32 v95, v5
	v_add_f32_e32 v0, v91, v0
	v_add_f32_e32 v0, v92, v0
	v_add_f32_e32 v0, v93, v0
	v_add_f32_e32 v0, v94, v0
	v_add_f32_e32 v0, v95, v0
	v_add_f32_e32 v160, v160, v0
	v_cvt_pk_bf16_f32 v3, v3, v4
	v_cvt_pk_bf16_f32 v4, v6, v7
	v_cvt_pk_bf16_f32 v5, v8, v9
	v_cvt_pk_bf16_f32 v6, v10, v11
	v_cvt_pk_bf16_f32 v7, v12, v13
	v_cvt_pk_bf16_f32 v8, v14, v15
	v_cvt_pk_bf16_f32 v9, v96, v97
	v_cvt_pk_bf16_f32 v10, v99, v100
	v_cvt_pk_bf16_f32 v11, v101, v102
	v_cvt_pk_bf16_f32 v12, v84, v85
	v_cvt_pk_bf16_f32 v13, v86, v87
	v_cvt_pk_bf16_f32 v80, v88, v89
	v_cvt_pk_bf16_f32 v81, v90, v91
	v_cvt_pk_bf16_f32 v82, v92, v93
	v_cvt_pk_bf16_f32 v83, v94, v95
	s_barrier
	v_add3_u32 v0, s50, v151, v146
	ds_read_b128 v[84:87], v0 offset:16384
	ds_read_b128 v[88:91], v0 offset:16416
	ds_read_b128 v[92:95], v0 offset:20992
	ds_read_b128 v[96:99], v0 offset:21024
	ds_read_b128 v[100:103], v0 offset:25600
	ds_read_b128 v[104:107], v0 offset:25632
	ds_read_b128 v[108:111], v0 offset:30208
	ds_read_b128 v[186:189], v0 offset:30240
	s_waitcnt lgkmcnt(7)
	v_mfma_f32_32x32x16_bf16 v[64:79], v[84:87], v[2:5], v[64:79]
	s_waitcnt lgkmcnt(5)
	v_mfma_f32_32x32x16_bf16 v[48:63], v[92:95], v[2:5], v[48:63]
	s_waitcnt lgkmcnt(3)
	v_mfma_f32_32x32x16_bf16 v[32:47], v[100:103], v[2:5], v[32:47]
	s_waitcnt lgkmcnt(1)
	v_mfma_f32_32x32x16_bf16 v[16:31], v[108:111], v[2:5], v[16:31]
	ds_read_b128 v[2:5], v0 offset:16448
	ds_read_b128 v[84:87], v0 offset:21056
	ds_read_b128 v[92:95], v0 offset:25664
	ds_read_b128 v[100:103], v0 offset:30272
	v_mfma_f32_32x32x16_bf16 v[64:79], v[88:91], v[6:9], v[64:79]
	v_mfma_f32_32x32x16_bf16 v[48:63], v[96:99], v[6:9], v[48:63]
	v_mfma_f32_32x32x16_bf16 v[32:47], v[104:107], v[6:9], v[32:47]
	s_waitcnt lgkmcnt(4)
	v_mfma_f32_32x32x16_bf16 v[16:31], v[186:189], v[6:9], v[16:31]
	ds_read_b128 v[6:9], v0 offset:16480
	ds_read_b128 v[88:91], v0 offset:21088
	ds_read_b128 v[96:99], v0 offset:25696
	ds_read_b128 v[104:107], v0 offset:30304
	s_waitcnt lgkmcnt(7)
	v_mfma_f32_32x32x16_bf16 v[64:79], v[2:5], v[10:13], v[64:79]
	s_waitcnt lgkmcnt(6)
	v_mfma_f32_32x32x16_bf16 v[48:63], v[84:87], v[10:13], v[48:63]
	s_waitcnt lgkmcnt(5)
	v_mfma_f32_32x32x16_bf16 v[32:47], v[92:95], v[10:13], v[32:47]
	s_waitcnt lgkmcnt(4)
	v_mfma_f32_32x32x16_bf16 v[16:31], v[100:103], v[10:13], v[16:31]
	s_waitcnt lgkmcnt(3)
	v_mfma_f32_32x32x16_bf16 v[64:79], v[6:9], v[80:83], v[64:79]
	s_waitcnt lgkmcnt(2)
	v_mfma_f32_32x32x16_bf16 v[48:63], v[88:91], v[80:83], v[48:63]
	s_waitcnt lgkmcnt(1)
	v_mfma_f32_32x32x16_bf16 v[32:47], v[96:99], v[80:83], v[32:47]
	s_waitcnt lgkmcnt(0)
	v_mfma_f32_32x32x16_bf16 v[16:31], v[104:107], v[80:83], v[16:31]
	s_add_u32 s8, s8, 0x80
	s_addc_u32 s9, s9, 0
	s_add_i32 s0, s0, 1
	s_cmpk_eq_i32 s8, 0x1180
	v_lshl_add_u64 v[162:163], v[162:163], 0, s[6:7]
	s_cbranch_scc1 .Lds_A298
	s_branch .Lds_A296
.Lds_B296:
	s_bitcmp1_b32 s0, 0
	s_cselect_b32 s50, 0x8800, 0
	v_add3_u32 v240, s50, v170, v171
	s_waitcnt vmcnt(3)
	ds_write_b128 v240, v[128:131]
	s_waitcnt vmcnt(2)
	ds_write_b128 v240, v[136:139] offset:8192
	v_add_u32_e32 v240, s50, v147
	v_add3_u32 v240, v240, v144, v172
	v_add_u32_e32 v242, 0x4000, v240
	s_waitcnt vmcnt(1)
	ds_write2_b64 v242, v[132:133], v[134:135] offset1:2
	v_add_co_u32_e32 v242, vcc, s47, v162
	v_add_u32_e32 v240, 0x6000, v240
	s_nop 0
	v_addc_co_u32_e32 v243, vcc, -1, v163, vcc
	s_waitcnt vmcnt(0)
	ds_write2_b64 v240, v[140:141], v[142:143] offset0:128 offset1:130
	s_waitcnt lgkmcnt(0)
	s_barrier
	global_load_dwordx4 v[128:131], v[242:243], off
	global_load_dwordx4 v[136:139], v[162:163], off
	v_lshl_add_u64 v[242:243], v[164:165], 0, s[8:9]
	v_add_co_u32_e32 v244, vcc, s38, v242
	s_nop 0
	s_nop 0
	v_addc_co_u32_e32 v245, vcc, 0, v243, vcc
	global_load_dwordx4 v[132:135], v[242:243], off offset:128
	global_load_dwordx4 v[140:143], v[244:245], off offset:128
	s_cmp_eq_u32 s0, 0
	s_cbranch_scc1 .Lds_Bfirst
	s_xor_b32 s98, s50, 0x8800
	v_add3_u32 v0, s98, v151, v146
	ds_read_b128 v[84:87], v0 offset:16384
	ds_read_b128 v[88:91], v0 offset:16416
	ds_read_b128 v[92:95], v0 offset:20992
	ds_read_b128 v[96:99], v0 offset:21024
	ds_read_b128 v[100:103], v0 offset:25600
	ds_read_b128 v[104:107], v0 offset:25632
	ds_read_b128 v[108:111], v0 offset:30208
	ds_read_b128 v[186:189], v0 offset:30240
	s_waitcnt lgkmcnt(7)
	v_mfma_f32_32x32x16_bf16 v[64:79], v[84:87], v[2:5], v[64:79]
	s_waitcnt lgkmcnt(5)
	v_mfma_f32_32x32x16_bf16 v[48:63], v[92:95], v[2:5], v[48:63]
	s_waitcnt lgkmcnt(3)
	v_mfma_f32_32x32x16_bf16 v[32:47], v[100:103], v[2:5], v[32:47]
	s_waitcnt lgkmcnt(1)
	v_mfma_f32_32x32x16_bf16 v[16:31], v[108:111], v[2:5], v[16:31]
	ds_read_b128 v[2:5], v0 offset:16448
	ds_read_b128 v[84:87], v0 offset:21056
	ds_read_b128 v[92:95], v0 offset:25664
	ds_read_b128 v[100:103], v0 offset:30272
	v_mfma_f32_32x32x16_bf16 v[64:79], v[88:91], v[6:9], v[64:79]
	v_mfma_f32_32x32x16_bf16 v[48:63], v[96:99], v[6:9], v[48:63]
	v_mfma_f32_32x32x16_bf16 v[32:47], v[104:107], v[6:9], v[32:47]
	s_waitcnt lgkmcnt(4)
	v_mfma_f32_32x32x16_bf16 v[16:31], v[186:189], v[6:9], v[16:31]
	ds_read_b128 v[6:9], v0 offset:16480
	ds_read_b128 v[88:91], v0 offset:21088
	ds_read_b128 v[96:99], v0 offset:25696
	ds_read_b128 v[104:107], v0 offset:30304
	s_waitcnt lgkmcnt(7)
	v_mfma_f32_32x32x16_bf16 v[64:79], v[2:5], v[10:13], v[64:79]
	s_waitcnt lgkmcnt(6)
	v_mfma_f32_32x32x16_bf16 v[48:63], v[84:87], v[10:13], v[48:63]
	s_waitcnt lgkmcnt(5)
	v_mfma_f32_32x32x16_bf16 v[32:47], v[92:95], v[10:13], v[32:47]
	s_waitcnt lgkmcnt(4)
	v_mfma_f32_32x32x16_bf16 v[16:31], v[100:103], v[10:13], v[16:31]
	s_waitcnt lgkmcnt(3)
	v_mfma_f32_32x32x16_bf16 v[64:79], v[6:9], v[80:83], v[64:79]
	s_waitcnt lgkmcnt(2)
	v_mfma_f32_32x32x16_bf16 v[48:63], v[88:91], v[80:83], v[48:63]
	s_waitcnt lgkmcnt(1)
	v_mfma_f32_32x32x16_bf16 v[32:47], v[96:99], v[80:83], v[32:47]
	s_waitcnt lgkmcnt(0)
	v_mfma_f32_32x32x16_bf16 v[16:31], v[104:107], v[80:83], v[16:31]
.Lds_Bfirst:
	v_add_u32_e32 v0, s50, v173
	v_add_u32_e32 v6, v0, v174
	v_add_u32_e32 v14, v0, v175
	ds_read_b128 v[2:5], v6
	ds_read_b128 v[6:9], v6 offset:8192
	ds_read_b128 v[10:13], v14
	ds_read_b128 v[186:189], v14 offset:8192
	v_add_u32_e32 v14, v0, v176
	v_add_u32_e32 v0, v0, v177
	ds_read_b128 v[190:193], v14
	ds_read_b128 v[194:197], v14 offset:8192
	ds_read_b128 v[198:201], v0
	ds_read_b128 v[202:205], v0 offset:8192
	s_waitcnt lgkmcnt(7)
	v_mfma_f32_32x32x16_bf16 v[96:111], v[2:5], v[124:127], 0
	s_waitcnt lgkmcnt(6)
	v_mfma_f32_32x32x16_bf16 v[80:95], v[6:9], v[124:127], 0
	s_waitcnt lgkmcnt(5)
	v_mfma_f32_32x32x16_bf16 v[96:111], v[10:13], v[120:123], v[96:111]
	s_waitcnt lgkmcnt(4)
	v_mfma_f32_32x32x16_bf16 v[80:95], v[186:189], v[120:123], v[80:95]
	s_waitcnt lgkmcnt(3)
	v_mfma_f32_32x32x16_bf16 v[96:111], v[190:193], v[116:119], v[96:111]
	s_waitcnt lgkmcnt(2)
	v_mfma_f32_32x32x16_bf16 v[80:95], v[194:197], v[116:119], v[80:95]
	s_waitcnt lgkmcnt(1)
	v_mfma_f32_32x32x16_bf16 v[96:111], v[198:201], v[112:115], v[96:111]
	s_waitcnt lgkmcnt(0)
	v_mfma_f32_32x32x16_bf16 v[80:95], v[202:205], v[112:115], v[80:95]
	s_barrier
	s_nop 9
	v_max_f32_e32 v0, v97, v97
	v_max_f32_e32 v2, v96, v96
	v_max_f32_e32 v0, v2, v0
	v_max3_f32 v0, v0, v98, v99
	v_max3_f32 v0, v0, v100, v101
	v_max3_f32 v0, v0, v102, v103
	v_max3_f32 v0, v0, v104, v105
	v_max3_f32 v0, v0, v106, v107
	v_max3_f32 v0, v0, v108, v109
	v_max3_f32 v0, v0, v110, v111
	v_max3_f32 v0, v0, v80, v81
	v_max3_f32 v0, v0, v82, v83
	v_max3_f32 v0, v0, v84, v85
	v_max3_f32 v0, v0, v86, v87
	v_max3_f32 v0, v0, v88, v89
	v_max3_f32 v0, v0, v90, v91
	v_max3_f32 v0, v0, v92, v93
	v_max3_f32 v0, v0, v94, v95
	v_mov_b32_e32 v2, v0
	s_nop 1
	v_permlane32_swap_b32_e32 v0, v2
	v_max_f32_e32 v2, v2, v2
	v_max_f32_e32 v0, v0, v0
	v_max_f32_e32 v0, v0, v2
	v_add_f32_e32 v2, 0x40b00000, v155
	v_cmp_gt_f32_e32 vcc, v0, v2
	s_cbranch_vccz .Lds_B295
	s_nop 0
	v_cndmask_b32_e32 v2, v155, v0, vcc
	v_sub_f32_e32 v0, v155, v2
	v_mul_f32_e32 v0, 0x3fb8aa3b, v0
	v_exp_f32_e32 v0, v0
	v_mov_b32_e32 v155, v2
	v_pk_mul_f32 v[78:79], v[78:79], v[0:1] op_sel_hi:[1,0]
	v_pk_mul_f32 v[76:77], v[76:77], v[0:1] op_sel_hi:[1,0]
	v_pk_mul_f32 v[74:75], v[74:75], v[0:1] op_sel_hi:[1,0]
	v_pk_mul_f32 v[72:73], v[72:73], v[0:1] op_sel_hi:[1,0]
	v_pk_mul_f32 v[70:71], v[70:71], v[0:1] op_sel_hi:[1,0]
	v_pk_mul_f32 v[68:69], v[68:69], v[0:1] op_sel_hi:[1,0]
	v_pk_mul_f32 v[66:67], v[66:67], v[0:1] op_sel_hi:[1,0]
	v_pk_mul_f32 v[64:65], v[64:65], v[0:1] op_sel_hi:[1,0]
	v_pk_mul_f32 v[62:63], v[62:63], v[0:1] op_sel_hi:[1,0]
	v_pk_mul_f32 v[60:61], v[60:61], v[0:1] op_sel_hi:[1,0]
	v_pk_mul_f32 v[58:59], v[58:59], v[0:1] op_sel_hi:[1,0]
	v_pk_mul_f32 v[56:57], v[56:57], v[0:1] op_sel_hi:[1,0]
	v_pk_mul_f32 v[54:55], v[54:55], v[0:1] op_sel_hi:[1,0]
	v_pk_mul_f32 v[52:53], v[52:53], v[0:1] op_sel_hi:[1,0]
	v_pk_mul_f32 v[50:51], v[50:51], v[0:1] op_sel_hi:[1,0]
	v_pk_mul_f32 v[48:49], v[48:49], v[0:1] op_sel_hi:[1,0]
	v_pk_mul_f32 v[46:47], v[46:47], v[0:1] op_sel_hi:[1,0]
	v_pk_mul_f32 v[44:45], v[44:45], v[0:1] op_sel_hi:[1,0]
	v_pk_mul_f32 v[42:43], v[42:43], v[0:1] op_sel_hi:[1,0]
	v_pk_mul_f32 v[40:41], v[40:41], v[0:1] op_sel_hi:[1,0]
	v_pk_mul_f32 v[38:39], v[38:39], v[0:1] op_sel_hi:[1,0]
	v_pk_mul_f32 v[36:37], v[36:37], v[0:1] op_sel_hi:[1,0]
	v_pk_mul_f32 v[34:35], v[34:35], v[0:1] op_sel_hi:[1,0]
	v_pk_mul_f32 v[32:33], v[32:33], v[0:1] op_sel_hi:[1,0]
	v_pk_mul_f32 v[30:31], v[30:31], v[0:1] op_sel_hi:[1,0]
	v_pk_mul_f32 v[28:29], v[28:29], v[0:1] op_sel_hi:[1,0]
	v_pk_mul_f32 v[26:27], v[26:27], v[0:1] op_sel_hi:[1,0]
	v_pk_mul_f32 v[24:25], v[24:25], v[0:1] op_sel_hi:[1,0]
	v_pk_mul_f32 v[22:23], v[22:23], v[0:1] op_sel_hi:[1,0]
	v_pk_mul_f32 v[20:21], v[20:21], v[0:1] op_sel_hi:[1,0]
	v_pk_mul_f32 v[18:19], v[18:19], v[0:1] op_sel_hi:[1,0]
	v_pk_mul_f32 v[16:17], v[16:17], v[0:1] op_sel_hi:[1,0]
	v_mul_f32_e32 v160, v160, v0
	s_branch .Lds_B295
.Lds_B295:
	v_mul_f32_e32 v161, 0xbfb8aa3b, v155
	v_fmamk_f32 v0, v96, 0x3fb8aa3b, v161
	v_exp_f32_e32 v0, v0
	v_fmamk_f32 v2, v97, 0x3fb8aa3b, v161
	v_exp_f32_e32 v2, v2
	v_fmamk_f32 v3, v98, 0x3fb8aa3b, v161
	v_exp_f32_e32 v3, v3
	v_fmamk_f32 v4, v99, 0x3fb8aa3b, v161
	v_exp_f32_e32 v4, v4
	v_fmamk_f32 v6, v100, 0x3fb8aa3b, v161
	v_add_f32_e32 v5, 0, v0
	v_exp_f32_e32 v6, v6
	v_fmamk_f32 v7, v101, 0x3fb8aa3b, v161
	v_add_f32_e32 v5, v2, v5
	v_exp_f32_e32 v7, v7
	v_fmamk_f32 v8, v102, 0x3fb8aa3b, v161
	v_add_f32_e32 v5, v3, v5
	v_exp_f32_e32 v8, v8
	v_fmamk_f32 v9, v103, 0x3fb8aa3b, v161
	v_add_f32_e32 v5, v4, v5
	v_exp_f32_e32 v9, v9
	v_fmamk_f32 v10, v104, 0x3fb8aa3b, v161
	v_add_f32_e32 v5, v6, v5
	v_exp_f32_e32 v10, v10
	v_fmamk_f32 v11, v105, 0x3fb8aa3b, v161
	v_add_f32_e32 v5, v7, v5
	v_exp_f32_e32 v11, v11
	v_fmamk_f32 v12, v106, 0x3fb8aa3b, v161
	v_add_f32_e32 v5, v8, v5
	v_exp_f32_e32 v12, v12
	v_fmamk_f32 v13, v107, 0x3fb8aa3b, v161
	v_add_f32_e32 v5, v9, v5
	v_exp_f32_e32 v13, v13
	v_fmamk_f32 v14, v108, 0x3fb8aa3b, v161
	v_add_f32_e32 v5, v10, v5
	v_exp_f32_e32 v14, v14
	v_fmamk_f32 v15, v109, 0x3fb8aa3b, v161
	v_add_f32_e32 v5, v11, v5
	v_exp_f32_e32 v15, v15
	v_fmamk_f32 v96, v110, 0x3fb8aa3b, v161
	v_add_f32_e32 v5, v12, v5
	v_exp_f32_e32 v96, v96
	v_fmamk_f32 v97, v111, 0x3fb8aa3b, v161
	v_add_f32_e32 v5, v13, v5
	v_exp_f32_e32 v97, v97
	v_add_f32_e32 v5, v14, v5
	v_add_f32_e32 v5, v15, v5
	v_add_f32_e32 v5, v96, v5
	v_add_f32_e32 v98, v97, v5
	v_fmamk_f32 v5, v80, 0x3fb8aa3b, v161
	v_exp_f32_e32 v99, v5
	v_fmamk_f32 v5, v81, 0x3fb8aa3b, v161
	v_exp_f32_e32 v100, v5
	v_fmamk_f32 v5, v82, 0x3fb8aa3b, v161
	v_exp_f32_e32 v101, v5
	v_fmamk_f32 v5, v83, 0x3fb8aa3b, v161
	v_exp_f32_e32 v102, v5
	v_fmamk_f32 v5, v84, 0x3fb8aa3b, v161
	v_exp_f32_e32 v84, v5
	v_fmamk_f32 v5, v85, 0x3fb8aa3b, v161
	v_cvt_pk_bf16_f32 v2, v0, v2
	v_add_f32_e32 v0, v99, v98
	v_exp_f32_e32 v85, v5
	v_fmamk_f32 v5, v86, 0x3fb8aa3b, v161
	v_add_f32_e32 v0, v100, v0
	v_exp_f32_e32 v86, v5
	v_fmamk_f32 v5, v87, 0x3fb8aa3b, v161
	v_add_f32_e32 v0, v101, v0
	v_exp_f32_e32 v87, v5
	v_fmamk_f32 v5, v88, 0x3fb8aa3b, v161
	v_add_f32_e32 v0, v102, v0
	v_exp_f32_e32 v88, v5
	v_fmamk_f32 v5, v89, 0x3fb8aa3b, v161
	v_add_f32_e32 v0, v84, v0
	v_exp_f32_e32 v89, v5
	v_fmamk_f32 v5, v90, 0x3fb8aa3b, v161
	v_add_f32_e32 v0, v85, v0
	v_exp_f32_e32 v90, v5
	v_fmamk_f32 v5, v91, 0x3fb8aa3b, v161
	v_add_f32_e32 v0, v86, v0
	v_exp_f32_e32 v91, v5
	v_fmamk_f32 v5, v92, 0x3fb8aa3b, v161
	v_add_f32_e32 v0, v87, v0
	v_exp_f32_e32 v92, v5
	v_fmamk_f32 v5, v93, 0x3fb8aa3b, v161
	v_add_f32_e32 v0, v88, v0
	v_exp_f32_e32 v93, v5
	v_fmamk_f32 v5, v94, 0x3fb8aa3b, v161
	v_add_f32_e32 v0, v89, v0
	v_exp_f32_e32 v94, v5
	v_fmamk_f32 v5, v95, 0x3fb8aa3b, v161
	v_add_f32_e32 v0, v90, v0
	v_exp_f32_e32 v95, v5
	v_add_f32_e32 v0, v91, v0
	v_add_f32_e32 v0, v92, v0
	v_add_f32_e32 v0, v93, v0
	v_add_f32_e32 v0, v94, v0
	v_add_f32_e32 v0, v95, v0
	v_add_f32_e32 v160, v160, v0
	v_cvt_pk_bf16_f32 v3, v3, v4
	v_cvt_pk_bf16_f32 v4, v6, v7
	v_cvt_pk_bf16_f32 v5, v8, v9
	v_cvt_pk_bf16_f32 v6, v10, v11
	v_cvt_pk_bf16_f32 v7, v12, v13
	v_cvt_pk_bf16_f32 v8, v14, v15
	v_cvt_pk_bf16_f32 v9, v96, v97
	v_cvt_pk_bf16_f32 v10, v99, v100
	v_cvt_pk_bf16_f32 v11, v101, v102
	v_cvt_pk_bf16_f32 v12, v84, v85
	v_cvt_pk_bf16_f32 v13, v86, v87
	v_cvt_pk_bf16_f32 v80, v88, v89
	v_cvt_pk_bf16_f32 v81, v90, v91
	v_cvt_pk_bf16_f32 v82, v92, v93
	v_cvt_pk_bf16_f32 v83, v94, v95
	s_add_u32 s8, s8, 0x80
	s_addc_u32 s9, s9, 0
	s_add_i32 s0, s0, 1
	s_cmpk_eq_i32 s8, 0x1180
	v_lshl_add_u64 v[162:163], v[162:163], 0, s[6:7]
	s_cbranch_scc1 .Lds_B298
	s_branch .Lds_B296

.Lds_A300:
	s_nop 0
	v_fmamk_f32 v0, v96, 0x3fb8aa3b, v161
	v_exp_f32_e32 v0, v0
	v_fmamk_f32 v2, v97, 0x3fb8aa3b, v161
	v_exp_f32_e32 v2, v2
	v_fmamk_f32 v3, v98, 0x3fb8aa3b, v161
	v_exp_f32_e32 v3, v3
	v_fmamk_f32 v4, v99, 0x3fb8aa3b, v161
	v_exp_f32_e32 v4, v4
	v_fmamk_f32 v6, v100, 0x3fb8aa3b, v161
	v_add_f32_e32 v5, 0, v0
	v_exp_f32_e32 v6, v6
	v_fmamk_f32 v7, v101, 0x3fb8aa3b, v161
	v_add_f32_e32 v5, v2, v5
	v_exp_f32_e32 v7, v7
	v_fmamk_f32 v8, v102, 0x3fb8aa3b, v161
	v_add_f32_e32 v5, v3, v5
	v_exp_f32_e32 v8, v8
	v_fmamk_f32 v9, v103, 0x3fb8aa3b, v161
	v_add_f32_e32 v5, v4, v5
	v_exp_f32_e32 v9, v9
	v_fmamk_f32 v10, v104, 0x3fb8aa3b, v161
	v_add_f32_e32 v5, v6, v5
	v_exp_f32_e32 v10, v10
	v_fmamk_f32 v11, v105, 0x3fb8aa3b, v161
	v_add_f32_e32 v5, v7, v5
	v_exp_f32_e32 v11, v11
	v_fmamk_f32 v12, v106, 0x3fb8aa3b, v161
	v_add_f32_e32 v5, v8, v5
	v_exp_f32_e32 v12, v12
	v_fmamk_f32 v13, v107, 0x3fb8aa3b, v161
	v_add_f32_e32 v5, v9, v5
	v_exp_f32_e32 v13, v13
	v_fmamk_f32 v14, v108, 0x3fb8aa3b, v161
	v_add_f32_e32 v5, v10, v5
	v_exp_f32_e32 v14, v14
	v_fmamk_f32 v15, v109, 0x3fb8aa3b, v161
	v_add_f32_e32 v5, v11, v5
	v_exp_f32_e32 v15, v15
	v_fmamk_f32 v96, v110, 0x3fb8aa3b, v161
	v_add_f32_e32 v5, v12, v5
	v_exp_f32_e32 v96, v96
	v_fmamk_f32 v97, v111, 0x3fb8aa3b, v161
	v_add_f32_e32 v5, v13, v5
	v_exp_f32_e32 v97, v97
	v_add_f32_e32 v5, v14, v5
	v_add_f32_e32 v5, v15, v5
	v_add_f32_e32 v5, v96, v5
	v_add_f32_e32 v98, v97, v5
	v_fmamk_f32 v5, v80, 0x3fb8aa3b, v161
	v_exp_f32_e32 v99, v5
	v_fmamk_f32 v5, v81, 0x3fb8aa3b, v161
	v_exp_f32_e32 v100, v5
	v_fmamk_f32 v5, v82, 0x3fb8aa3b, v161
	v_exp_f32_e32 v101, v5
	v_fmamk_f32 v5, v83, 0x3fb8aa3b, v161
	v_exp_f32_e32 v102, v5
	v_fmamk_f32 v5, v84, 0x3fb8aa3b, v161
	v_exp_f32_e32 v84, v5
	v_fmamk_f32 v5, v85, 0x3fb8aa3b, v161
	v_cvt_pk_bf16_f32 v2, v0, v2
	v_add_f32_e32 v0, v99, v98
	v_exp_f32_e32 v85, v5
	v_fmamk_f32 v5, v86, 0x3fb8aa3b, v161
	v_add_f32_e32 v0, v100, v0
	v_exp_f32_e32 v86, v5
	v_fmamk_f32 v5, v87, 0x3fb8aa3b, v161
	v_add_f32_e32 v0, v101, v0
	v_exp_f32_e32 v87, v5
	v_fmamk_f32 v5, v88, 0x3fb8aa3b, v161
	v_add_f32_e32 v0, v102, v0
	v_exp_f32_e32 v88, v5
	v_fmamk_f32 v5, v89, 0x3fb8aa3b, v161
	v_add_f32_e32 v0, v84, v0
	v_exp_f32_e32 v89, v5
	v_fmamk_f32 v5, v90, 0x3fb8aa3b, v161
	v_add_f32_e32 v0, v85, v0
	v_exp_f32_e32 v90, v5
	v_fmamk_f32 v5, v91, 0x3fb8aa3b, v161
	v_add_f32_e32 v0, v86, v0
	v_exp_f32_e32 v91, v5
	v_fmamk_f32 v5, v92, 0x3fb8aa3b, v161
	v_add_f32_e32 v0, v87, v0
	v_exp_f32_e32 v92, v5
	v_fmamk_f32 v5, v93, 0x3fb8aa3b, v161
	v_add_f32_e32 v0, v88, v0
	v_exp_f32_e32 v93, v5
	v_fmamk_f32 v5, v94, 0x3fb8aa3b, v161
	v_add_f32_e32 v0, v89, v0
	v_exp_f32_e32 v94, v5
	v_fmac_f32_e32 v161, 0x3fb8aa3b, v95
	v_add_f32_e32 v0, v90, v0
	v_exp_f32_e32 v95, v161
	v_add_f32_e32 v0, v91, v0
	v_add_f32_e32 v0, v92, v0
	v_add_f32_e32 v0, v93, v0
	v_add_f32_e32 v0, v94, v0
	v_add_f32_e32 v0, v95, v0
	v_cvt_pk_bf16_f32 v5, v8, v9
	v_cvt_pk_bf16_f32 v8, v14, v15
	v_add_f32_e32 v0, v160, v0
	v_mul_i32_i24_e32 v14, 0xffffff90, v167
	v_cvt_pk_bf16_f32 v3, v3, v4
	v_cvt_pk_bf16_f32 v4, v6, v7
	v_cvt_pk_bf16_f32 v6, v10, v11
	v_cvt_pk_bf16_f32 v7, v12, v13
	v_cvt_pk_bf16_f32 v9, v96, v97
	v_cvt_pk_bf16_f32 v10, v99, v100
	v_cvt_pk_bf16_f32 v11, v101, v102
	v_cvt_pk_bf16_f32 v12, v84, v85
	v_cvt_pk_bf16_f32 v13, v86, v87
	v_cvt_pk_bf16_f32 v80, v88, v89
	v_cvt_pk_bf16_f32 v81, v90, v91
	v_cvt_pk_bf16_f32 v82, v92, v93
	v_cvt_pk_bf16_f32 v83, v94, v95
	s_barrier
	v_add3_u32 v14, v173, v14, v146
	ds_read_b128 v[84:87], v14 offset:51200
	ds_read_b128 v[88:91], v14 offset:51232
	ds_read_b128 v[92:95], v14 offset:55808
	ds_read_b128 v[96:99], v14 offset:55840
	ds_read_b128 v[100:103], v14 offset:60416
	ds_read_b128 v[104:107], v14 offset:60448
	ds_read_b128 v[108:111], v14 offset:65024
	ds_read_b128 v[112:115], v14 offset:65056
	s_waitcnt lgkmcnt(7)
	v_mfma_f32_32x32x16_bf16 v[64:79], v[84:87], v[2:5], v[64:79]
	s_waitcnt lgkmcnt(5)
	v_mfma_f32_32x32x16_bf16 v[48:63], v[92:95], v[2:5], v[48:63]
	s_waitcnt lgkmcnt(3)
	v_mfma_f32_32x32x16_bf16 v[32:47], v[100:103], v[2:5], v[32:47]
	s_waitcnt lgkmcnt(1)
	v_mfma_f32_32x32x16_bf16 v[16:31], v[108:111], v[2:5], v[16:31]
	ds_read_b128 v[2:5], v14 offset:51264
	ds_read_b128 v[84:87], v14 offset:55872
	ds_read_b128 v[92:95], v14 offset:60480
	ds_read_b128 v[100:103], v14 offset:65088
	v_mfma_f32_32x32x16_bf16 v[64:79], v[88:91], v[6:9], v[64:79]
	v_mfma_f32_32x32x16_bf16 v[48:63], v[96:99], v[6:9], v[48:63]
	v_mfma_f32_32x32x16_bf16 v[32:47], v[104:107], v[6:9], v[32:47]
	s_waitcnt lgkmcnt(4)
	v_mfma_f32_32x32x16_bf16 v[16:31], v[112:115], v[6:9], v[16:31]
	ds_read_b128 v[6:9], v14 offset:51296
	ds_read_b128 v[88:91], v14 offset:55904
	ds_read_b128 v[96:99], v14 offset:60512
	ds_read_b128 v[104:107], v14 offset:65120
	s_waitcnt lgkmcnt(7)
	v_mfma_f32_32x32x16_bf16 v[64:79], v[2:5], v[10:13], v[64:79]
	s_waitcnt lgkmcnt(6)
	v_mfma_f32_32x32x16_bf16 v[48:63], v[84:87], v[10:13], v[48:63]
	s_waitcnt lgkmcnt(5)
	v_mfma_f32_32x32x16_bf16 v[32:47], v[92:95], v[10:13], v[32:47]
	s_waitcnt lgkmcnt(4)
	v_mfma_f32_32x32x16_bf16 v[16:31], v[100:103], v[10:13], v[16:31]
	s_waitcnt lgkmcnt(3)
	v_mfma_f32_32x32x16_bf16 v[64:79], v[6:9], v[80:83], v[64:79]
	s_waitcnt lgkmcnt(2)
	v_mfma_f32_32x32x16_bf16 v[48:63], v[88:91], v[80:83], v[48:63]
	s_waitcnt lgkmcnt(1)
	v_mfma_f32_32x32x16_bf16 v[32:47], v[96:99], v[80:83], v[32:47]
	s_waitcnt lgkmcnt(0)
	v_mfma_f32_32x32x16_bf16 v[16:31], v[104:107], v[80:83], v[16:31]
	s_branch .Lds_join
.Lds_B298:
	v_add_u32_e32 v240, v170, v171
	s_waitcnt vmcnt(3)
	ds_write_b128 v240, v[128:131] offset:34816
	s_waitcnt vmcnt(2)
	ds_write_b128 v240, v[136:139] offset:43008
	v_add3_u32 v240, v147, v144, v172
	v_add_u32_e32 v242, 0xc800, v240
	v_add_u32_e32 v240, 0xe800, v240
	s_waitcnt vmcnt(1)
	ds_write2_b64 v242, v[132:133], v[134:135] offset1:2
	s_waitcnt vmcnt(0)
	ds_write2_b64 v240, v[140:141], v[142:143] offset0:128 offset1:130
	s_waitcnt lgkmcnt(0)
	s_barrier
	s_mov_b32 s98, 0
	v_add3_u32 v0, s98, v151, v146
	ds_read_b128 v[84:87], v0 offset:16384
	ds_read_b128 v[88:91], v0 offset:16416
	ds_read_b128 v[92:95], v0 offset:20992
	ds_read_b128 v[96:99], v0 offset:21024
	ds_read_b128 v[100:103], v0 offset:25600
	ds_read_b128 v[104:107], v0 offset:25632
	ds_read_b128 v[108:111], v0 offset:30208
	ds_read_b128 v[186:189], v0 offset:30240
	s_waitcnt lgkmcnt(7)
	v_mfma_f32_32x32x16_bf16 v[64:79], v[84:87], v[2:5], v[64:79]
	s_waitcnt lgkmcnt(5)
	v_mfma_f32_32x32x16_bf16 v[48:63], v[92:95], v[2:5], v[48:63]
	s_waitcnt lgkmcnt(3)
	v_mfma_f32_32x32x16_bf16 v[32:47], v[100:103], v[2:5], v[32:47]
	s_waitcnt lgkmcnt(1)
	v_mfma_f32_32x32x16_bf16 v[16:31], v[108:111], v[2:5], v[16:31]
	ds_read_b128 v[2:5], v0 offset:16448
	ds_read_b128 v[84:87], v0 offset:21056
	ds_read_b128 v[92:95], v0 offset:25664
	ds_read_b128 v[100:103], v0 offset:30272
	v_mfma_f32_32x32x16_bf16 v[64:79], v[88:91], v[6:9], v[64:79]
	v_mfma_f32_32x32x16_bf16 v[48:63], v[96:99], v[6:9], v[48:63]
	v_mfma_f32_32x32x16_bf16 v[32:47], v[104:107], v[6:9], v[32:47]
	s_waitcnt lgkmcnt(4)
	v_mfma_f32_32x32x16_bf16 v[16:31], v[186:189], v[6:9], v[16:31]
	ds_read_b128 v[6:9], v0 offset:16480
	ds_read_b128 v[88:91], v0 offset:21088
	ds_read_b128 v[96:99], v0 offset:25696
	ds_read_b128 v[104:107], v0 offset:30304
	s_waitcnt lgkmcnt(7)
	v_mfma_f32_32x32x16_bf16 v[64:79], v[2:5], v[10:13], v[64:79]
	s_waitcnt lgkmcnt(6)
	v_mfma_f32_32x32x16_bf16 v[48:63], v[84:87], v[10:13], v[48:63]
	s_waitcnt lgkmcnt(5)
	v_mfma_f32_32x32x16_bf16 v[32:47], v[92:95], v[10:13], v[32:47]
	s_waitcnt lgkmcnt(4)
	v_mfma_f32_32x32x16_bf16 v[16:31], v[100:103], v[10:13], v[16:31]
	s_waitcnt lgkmcnt(3)
	v_mfma_f32_32x32x16_bf16 v[64:79], v[6:9], v[80:83], v[64:79]
	s_waitcnt lgkmcnt(2)
	v_mfma_f32_32x32x16_bf16 v[48:63], v[88:91], v[80:83], v[48:63]
	s_waitcnt lgkmcnt(1)
	v_mfma_f32_32x32x16_bf16 v[32:47], v[96:99], v[80:83], v[32:47]
	s_waitcnt lgkmcnt(0)
	v_mfma_f32_32x32x16_bf16 v[16:31], v[104:107], v[80:83], v[16:31]
	ds_read_b128 v[2:5], v179 offset:34816
	ds_read_b128 v[6:9], v179 offset:43008
	ds_read_b128 v[10:13], v180 offset:34816
	ds_read_b128 v[128:131], v180 offset:43008
	ds_read_b128 v[132:135], v181 offset:34816
	ds_read_b128 v[136:139], v181 offset:43008
	ds_read_b128 v[140:143], v182 offset:34816
	ds_read_b128 v[162:165], v182 offset:43008
	s_waitcnt lgkmcnt(7)
	v_mfma_f32_32x32x16_bf16 v[96:111], v[2:5], v[124:127], 0
	s_waitcnt lgkmcnt(6)
	v_mfma_f32_32x32x16_bf16 v[80:95], v[6:9], v[124:127], 0
	s_waitcnt lgkmcnt(5)
	v_mfma_f32_32x32x16_bf16 v[96:111], v[10:13], v[120:123], v[96:111]
	s_waitcnt lgkmcnt(4)
	v_mfma_f32_32x32x16_bf16 v[80:95], v[128:131], v[120:123], v[80:95]
	s_waitcnt lgkmcnt(3)
	v_mfma_f32_32x32x16_bf16 v[96:111], v[132:135], v[116:119], v[96:111]
	s_waitcnt lgkmcnt(2)
	v_mfma_f32_32x32x16_bf16 v[80:95], v[136:139], v[116:119], v[80:95]
	s_waitcnt lgkmcnt(1)
	v_mfma_f32_32x32x16_bf16 v[96:111], v[140:143], v[112:115], v[96:111]
	s_waitcnt lgkmcnt(0)
	v_mfma_f32_32x32x16_bf16 v[80:95], v[162:165], v[112:115], v[80:95]
	s_barrier
	s_nop 9
	v_max_f32_e32 v0, v97, v97
	v_max_f32_e32 v2, v96, v96
	v_max_f32_e32 v0, v2, v0
	v_max3_f32 v0, v0, v98, v99
	v_max3_f32 v0, v0, v100, v101
	v_max3_f32 v0, v0, v102, v103
	v_max3_f32 v0, v0, v104, v105
	v_max3_f32 v0, v0, v106, v107
	v_max3_f32 v0, v0, v108, v109
	v_max3_f32 v0, v0, v110, v111
	v_max3_f32 v0, v0, v80, v81
	v_max3_f32 v0, v0, v82, v83
	v_max3_f32 v0, v0, v84, v85
	v_max3_f32 v0, v0, v86, v87
	v_max3_f32 v0, v0, v88, v89
	v_max3_f32 v0, v0, v90, v91
	v_max3_f32 v0, v0, v92, v93
	v_max3_f32 v0, v0, v94, v95
	v_mov_b32_e32 v2, v0
	s_nop 1
	v_permlane32_swap_b32_e32 v0, v2
	v_max_f32_e32 v2, v2, v2
	v_max_f32_e32 v0, v0, v0
	v_max_f32_e32 v0, v0, v2
	v_add_f32_e32 v2, 0x40b00000, v155
	v_cmp_gt_f32_e32 vcc, v0, v2
	s_cbranch_vccz .Lds_B300
	s_nop 0
	v_cndmask_b32_e32 v161, v155, v0, vcc
	v_sub_f32_e32 v0, v155, v161
	v_mul_f32_e32 v0, 0x3fb8aa3b, v0
	v_exp_f32_e32 v144, v0
	s_nop 0
	v_pk_mul_f32 v[78:79], v[78:79], v[144:145] op_sel_hi:[1,0]
	v_pk_mul_f32 v[76:77], v[76:77], v[144:145] op_sel_hi:[1,0]
	v_pk_mul_f32 v[74:75], v[74:75], v[144:145] op_sel_hi:[1,0]
	v_pk_mul_f32 v[72:73], v[72:73], v[144:145] op_sel_hi:[1,0]
	v_pk_mul_f32 v[70:71], v[70:71], v[144:145] op_sel_hi:[1,0]
	v_pk_mul_f32 v[68:69], v[68:69], v[144:145] op_sel_hi:[1,0]
	v_pk_mul_f32 v[66:67], v[66:67], v[144:145] op_sel_hi:[1,0]
	v_pk_mul_f32 v[64:65], v[64:65], v[144:145] op_sel_hi:[1,0]
	v_pk_mul_f32 v[62:63], v[62:63], v[144:145] op_sel_hi:[1,0]
	v_pk_mul_f32 v[60:61], v[60:61], v[144:145] op_sel_hi:[1,0]
	v_pk_mul_f32 v[58:59], v[58:59], v[144:145] op_sel_hi:[1,0]
	v_pk_mul_f32 v[56:57], v[56:57], v[144:145] op_sel_hi:[1,0]
	v_pk_mul_f32 v[54:55], v[54:55], v[144:145] op_sel_hi:[1,0]
	v_pk_mul_f32 v[52:53], v[52:53], v[144:145] op_sel_hi:[1,0]
	v_pk_mul_f32 v[50:51], v[50:51], v[144:145] op_sel_hi:[1,0]
	v_pk_mul_f32 v[48:49], v[48:49], v[144:145] op_sel_hi:[1,0]
	v_pk_mul_f32 v[46:47], v[46:47], v[144:145] op_sel_hi:[1,0]
	v_pk_mul_f32 v[44:45], v[44:45], v[144:145] op_sel_hi:[1,0]
	v_pk_mul_f32 v[42:43], v[42:43], v[144:145] op_sel_hi:[1,0]
	v_pk_mul_f32 v[40:41], v[40:41], v[144:145] op_sel_hi:[1,0]
	v_pk_mul_f32 v[38:39], v[38:39], v[144:145] op_sel_hi:[1,0]
	v_pk_mul_f32 v[36:37], v[36:37], v[144:145] op_sel_hi:[1,0]
	v_pk_mul_f32 v[34:35], v[34:35], v[144:145] op_sel_hi:[1,0]
	v_pk_mul_f32 v[32:33], v[32:33], v[144:145] op_sel_hi:[1,0]
	v_pk_mul_f32 v[30:31], v[30:31], v[144:145] op_sel_hi:[1,0]
	v_pk_mul_f32 v[28:29], v[28:29], v[144:145] op_sel_hi:[1,0]
	v_pk_mul_f32 v[26:27], v[26:27], v[144:145] op_sel_hi:[1,0]
	v_pk_mul_f32 v[24:25], v[24:25], v[144:145] op_sel_hi:[1,0]
	v_pk_mul_f32 v[22:23], v[22:23], v[144:145] op_sel_hi:[1,0]
	v_pk_mul_f32 v[20:21], v[20:21], v[144:145] op_sel_hi:[1,0]
	v_pk_mul_f32 v[18:19], v[18:19], v[144:145] op_sel_hi:[1,0]
	v_pk_mul_f32 v[16:17], v[16:17], v[144:145] op_sel_hi:[1,0]
	v_pk_mul_f32 v[160:161], v[160:161], v[144:145]

.Lds_join:
	v_mov_b32_e32 v2, v0
	s_nop 1
	v_permlane32_swap_b32_e32 v0, v2
	v_add_f32_e32 v0, v0, v2
	v_div_scale_f32 v2, s[8:9], v0, v0, 1.0
	v_rcp_f32_e32 v3, v2
	s_barrier
	v_fma_f32 v4, -v2, v3, 1.0
	v_fmac_f32_e32 v3, v4, v3
	v_div_scale_f32 v4, vcc, 1.0, v0, 1.0
	v_mul_f32_e32 v5, v4, v3
	v_fma_f32 v6, -v2, v5, v4
	v_fmac_f32_e32 v5, v6, v3
	v_fma_f32 v2, -v2, v5, v4
	v_div_fmas_f32 v2, v2, v3, v5
	v_div_fixup_f32 v0, v2, v0, 1.0
	s_and_b64 vcc, exec, s[4:5]
	v_lshl_add_u32 v2, v166, 2, s13
	s_cbranch_vccz .LBB0_302
	global_load_dword v3, v1, s[24:25]
	s_waitcnt vmcnt(0)
	v_mul_f32_e32 v3, v0, v3
	v_mul_f32_e32 v4, v64, v3
	v_mul_f32_e32 v5, v65, v3
	v_mul_f32_e32 v6, v66, v3
	v_mul_f32_e32 v7, v67, v3
	v_mul_f32_e32 v8, v68, v3
	v_mul_f32_e32 v9, v69, v3
	v_mul_f32_e32 v10, v70, v3
	v_mul_f32_e32 v11, v71, v3
	v_mul_f32_e32 v12, v72, v3
	v_mul_f32_e32 v13, v73, v3
	v_mul_f32_e32 v14, v74, v3
	v_mul_f32_e32 v15, v75, v3
	v_mul_f32_e32 v80, v76, v3
	v_mul_f32_e32 v81, v77, v3
	v_mul_f32_e32 v82, v78, v3
	v_mul_f32_e32 v83, v79, v3
	v_mul_f32_e32 v84, v48, v3
	v_mul_f32_e32 v85, v49, v3
	v_mul_f32_e32 v86, v50, v3
	v_mul_f32_e32 v87, v51, v3
	v_mul_f32_e32 v88, v52, v3
	v_mul_f32_e32 v89, v53, v3
	v_mul_f32_e32 v90, v54, v3
	v_mul_f32_e32 v91, v55, v3
	v_mul_f32_e32 v92, v56, v3
	v_mul_f32_e32 v93, v57, v3
	v_mul_f32_e32 v94, v58, v3
	v_mul_f32_e32 v95, v59, v3
	v_mul_f32_e32 v96, v60, v3
	v_mul_f32_e32 v97, v61, v3
	v_mul_f32_e32 v98, v62, v3
	v_mul_f32_e32 v99, v63, v3
	v_mul_f32_e32 v100, v32, v3
	v_mul_f32_e32 v101, v33, v3
	v_mul_f32_e32 v102, v34, v3
	v_mul_f32_e32 v103, v35, v3
	v_mul_f32_e32 v104, v36, v3
	v_mul_f32_e32 v105, v37, v3
	v_mul_f32_e32 v106, v38, v3
	v_mul_f32_e32 v107, v39, v3
	v_mul_f32_e32 v108, v40, v3
	v_mul_f32_e32 v109, v41, v3
	v_mul_f32_e32 v110, v42, v3
	v_mul_f32_e32 v111, v43, v3
	v_mul_f32_e32 v112, v44, v3
	v_mul_f32_e32 v113, v45, v3
	v_mul_f32_e32 v114, v46, v3
	v_mul_f32_e32 v115, v47, v3
	v_mul_f32_e32 v116, v16, v3
	v_mul_f32_e32 v117, v17, v3
	v_mul_f32_e32 v118, v18, v3
	v_mul_f32_e32 v119, v19, v3
	v_mul_f32_e32 v120, v20, v3
	v_mul_f32_e32 v121, v21, v3
	ds_write2st64_b32 v2, v4, v5 offset1:1
	ds_write2st64_b32 v2, v6, v7 offset0:2 offset1:3
	ds_write2st64_b32 v2, v8, v9 offset0:4 offset1:5
	ds_write2st64_b32 v2, v10, v11 offset0:6 offset1:7
	ds_write2st64_b32 v2, v12, v13 offset0:8 offset1:9
	ds_write2st64_b32 v2, v14, v15 offset0:10 offset1:11
	ds_write2st64_b32 v2, v80, v81 offset0:12 offset1:13
	ds_write2st64_b32 v2, v82, v83 offset0:14 offset1:15
	ds_write2st64_b32 v2, v84, v85 offset0:16 offset1:17
	ds_write2st64_b32 v2, v86, v87 offset0:18 offset1:19
	ds_write2st64_b32 v2, v88, v89 offset0:20 offset1:21
	ds_write2st64_b32 v2, v90, v91 offset0:22 offset1:23
	ds_write2st64_b32 v2, v92, v93 offset0:24 offset1:25
	ds_write2st64_b32 v2, v94, v95 offset0:26 offset1:27
	ds_write2st64_b32 v2, v96, v97 offset0:28 offset1:29
	ds_write2st64_b32 v2, v98, v99 offset0:30 offset1:31
	ds_write2st64_b32 v2, v100, v101 offset0:32 offset1:33
	ds_write2st64_b32 v2, v102, v103 offset0:34 offset1:35
	ds_write2st64_b32 v2, v104, v105 offset0:36 offset1:37
	ds_write2st64_b32 v2, v106, v107 offset0:38 offset1:39
	ds_write2st64_b32 v2, v108, v109 offset0:40 offset1:41
	ds_write2st64_b32 v2, v110, v111 offset0:42 offset1:43
	ds_write2st64_b32 v2, v112, v113 offset0:44 offset1:45
	ds_write2st64_b32 v2, v114, v115 offset0:46 offset1:47
	ds_write2st64_b32 v2, v116, v117 offset0:48 offset1:49
	ds_write2st64_b32 v2, v118, v119 offset0:50 offset1:51
	ds_write2st64_b32 v2, v120, v121 offset0:52 offset1:53
	v_mul_f32_e32 v4, v22, v3
	v_mul_f32_e32 v5, v23, v3
	ds_write2st64_b32 v2, v4, v5 offset0:54 offset1:55
	v_mul_f32_e32 v4, v24, v3
	v_mul_f32_e32 v5, v25, v3
	ds_write2st64_b32 v2, v4, v5 offset0:56 offset1:57
	v_mul_f32_e32 v4, v26, v3
	v_mul_f32_e32 v5, v27, v3
	ds_write2st64_b32 v2, v4, v5 offset0:58 offset1:59
	v_mul_f32_e32 v4, v28, v3
	v_mul_f32_e32 v5, v29, v3
	ds_write2st64_b32 v2, v4, v5 offset0:60 offset1:61
	v_mul_f32_e32 v4, v30, v3
	v_mul_f32_e32 v3, v31, v3
	ds_write2st64_b32 v2, v4, v3 offset0:62 offset1:63

	.amdhsa_kernel _Z14fwd_megakernel6Paramsii
		.amdhsa_group_segment_fixed_size 143376
		.amdhsa_private_segment_fixed_size 0
		.amdhsa_kernarg_size 560
		.amdhsa_user_sgpr_count 2
		.amdhsa_user_sgpr_dispatch_ptr 0
		.amdhsa_user_sgpr_queue_ptr 0
		.amdhsa_user_sgpr_kernarg_segment_ptr 1
		.amdhsa_user_sgpr_dispatch_id 0
		.amdhsa_user_sgpr_kernarg_preload_length 0
		.amdhsa_user_sgpr_kernarg_preload_offset 0
		.amdhsa_user_sgpr_private_segment_size 0
		.amdhsa_uses_dynamic_stack 0
		.amdhsa_enable_private_segment 0
		.amdhsa_system_sgpr_workgroup_id_x 1
		.amdhsa_system_sgpr_workgroup_id_y 0
		.amdhsa_system_sgpr_workgroup_id_z 0
		.amdhsa_system_sgpr_workgroup_info 0
		.amdhsa_system_vgpr_workitem_id 2
		.amdhsa_next_free_vgpr 256
		.amdhsa_next_free_sgpr 102
		.amdhsa_accum_offset 256
		.amdhsa_reserve_vcc 1
		.amdhsa_float_round_mode_32 0
		.amdhsa_float_round_mode_16_64 0
		.amdhsa_float_denorm_mode_32 3
		.amdhsa_float_denorm_mode_16_64 3
		.amdhsa_dx10_clamp 1
		.amdhsa_ieee_mode 1
		.amdhsa_fp16_overflow 0
		.amdhsa_tg_split 0
		.amdhsa_exception_fp_ieee_invalid_op 0
		.amdhsa_exception_fp_denorm_src 0
		.amdhsa_exception_fp_ieee_div_zero 0
		.amdhsa_exception_fp_ieee_overflow 0
		.amdhsa_exception_fp_ieee_underflow 0
		.amdhsa_exception_fp_ieee_inexact 0
		.amdhsa_exception_int_div_zero 0
	.end_amdhsa_kernel

amdhsa.kernels:
  - .agpr_count:     0
    .args:
      - .offset:         0
        .size:           296
        .value_kind:     by_value
      - .offset:         296
        .size:           4
        .value_kind:     by_value
      - .offset:         300
        .size:           4
        .value_kind:     by_value
      - .offset:         304
        .size:           4
        .value_kind:     hidden_block_count_x
      - .offset:         308
        .size:           4
        .value_kind:     hidden_block_count_y
      - .offset:         312
        .size:           4
        .value_kind:     hidden_block_count_z
      - .offset:         316
        .size:           2
        .value_kind:     hidden_group_size_x
      - .offset:         318
        .size:           2
        .value_kind:     hidden_group_size_y
      - .offset:         320
        .size:           2
        .value_kind:     hidden_group_size_z
      - .offset:         322
        .size:           2
        .value_kind:     hidden_remainder_x
      - .offset:         324
        .size:           2
        .value_kind:     hidden_remainder_y
      - .offset:         326
        .size:           2
        .value_kind:     hidden_remainder_z
      - .offset:         344
        .size:           8
        .value_kind:     hidden_global_offset_x
      - .offset:         352
        .size:           8
        .value_kind:     hidden_global_offset_y
      - .offset:         360
        .size:           8
        .value_kind:     hidden_global_offset_z
      - .offset:         368
        .size:           2
        .value_kind:     hidden_grid_dims
      - .offset:         392
        .size:           8
        .value_kind:     hidden_multigrid_sync_arg
    .group_segment_fixed_size: 143376
    .kernarg_segment_align: 8
    .kernarg_segment_size: 560
    .language:       OpenCL C
    .language_version:
      - 2
      - 0
    .max_flat_workgroup_size: 512
    .name:           _Z14fwd_megakernel6Paramsii
    .private_segment_fixed_size: 0
    .sgpr_count:     108
    .sgpr_spill_count: 65
    .symbol:         _Z14fwd_megakernel6Paramsii.kd
    .uniform_work_group_size: 1
    .uses_dynamic_stack: false
    .vgpr_count:     256
    .vgpr_spill_count: 0
    .wavefront_size: 64
